# kv-tile and NSA-q GEMM epilogues: 8 per-row-group sum-of-squares loads hoisted and issued together (removes 7 serial load+store-drain waits per tile), on top of conv-tile de-serialisation
# baseline (speedup 1.0000x reference)
.LBB0_706:
	s_add_i32 s11, s10, 64
	s_min_u32 s13, s11, 0x3e0
	s_lshl_b32 s16, s13, 1
	v_lshl_add_u64 v[172:173], v[154:155], 0, s[16:17]
	v_lshl_add_u64 v[176:177], v[158:159], 0, s[16:17]
	v_lshl_add_u64 v[180:181], v[160:161], 0, s[16:17]
	v_lshl_add_u64 v[184:185], v[162:163], 0, s[16:17]
	v_lshl_add_u64 v[188:189], v[156:157], 0, s[16:17]
	v_lshl_add_u64 v[192:193], v[164:165], 0, s[16:17]
	global_load_dwordx4 v[172:175], v[172:173], off
	ds_read_b128 v[196:199], v171 offset:32768
	global_load_dwordx4 v[176:179], v[176:177], off
	ds_read_b128 v[200:203], v171 offset:33792
	global_load_dwordx4 v[180:183], v[180:181], off
	ds_read_b128 v[204:207], v171 offset:34816
	global_load_dwordx4 v[184:187], v[184:185], off
	ds_read_b128 v[208:211], v171 offset:35840
	global_load_dwordx4 v[188:191], v[188:189], off
	ds_read_b128 v[212:215], v169
	global_load_dwordx4 v[192:195], v[192:193], off
	ds_read_b128 v[216:219], v169 offset:1024
	ds_read_b128 v[222:225], v169 offset:2048
	ds_read_b128 v[226:229], v169 offset:3072
	ds_read_b128 v[230:233], v169 offset:4096
	ds_read_b128 v[234:237], v169 offset:5120
	ds_read_b128 v[238:241], v169 offset:6144
	ds_read_b128 v[242:245], v169 offset:7168
	s_setprio 1
	s_waitcnt lgkmcnt(7)
	v_mfma_f32_16x16x32_bf16 v[148:151], v[196:199], v[212:215], v[148:151]
	v_mfma_f32_16x16x32_bf16 v[144:147], v[200:203], v[212:215], v[144:147]
	v_mfma_f32_16x16x32_bf16 v[140:143], v[204:207], v[212:215], v[140:143]
	v_mfma_f32_16x16x32_bf16 v[136:139], v[208:211], v[212:215], v[136:139]
	s_waitcnt vmcnt(11)
	ds_write_b128 v152, v[112:115] offset:16384
	s_waitcnt lgkmcnt(7)
	v_mfma_f32_16x16x32_bf16 v[108:111], v[196:199], v[216:219], v[108:111]
	v_mfma_f32_16x16x32_bf16 v[104:107], v[200:203], v[216:219], v[104:107]
	v_mfma_f32_16x16x32_bf16 v[100:103], v[204:207], v[216:219], v[100:103]
	v_mfma_f32_16x16x32_bf16 v[96:99], v[208:211], v[216:219], v[96:99]
	s_waitcnt vmcnt(9)
	ds_write_b128 v152, v[120:123] offset:20480
	s_waitcnt lgkmcnt(7)
	v_mfma_f32_16x16x32_bf16 v[92:95], v[196:199], v[222:225], v[92:95]
	v_mfma_f32_16x16x32_bf16 v[88:91], v[200:203], v[222:225], v[88:91]
	v_mfma_f32_16x16x32_bf16 v[84:87], v[204:207], v[222:225], v[84:87]
	v_mfma_f32_16x16x32_bf16 v[80:83], v[208:211], v[222:225], v[80:83]
	s_waitcnt vmcnt(8)
	ds_write_b128 v152, v[124:127] offset:24576
	s_waitcnt lgkmcnt(7)
	v_mfma_f32_16x16x32_bf16 v[76:79], v[196:199], v[226:229], v[76:79]
	v_mfma_f32_16x16x32_bf16 v[72:75], v[200:203], v[226:229], v[72:75]
	v_mfma_f32_16x16x32_bf16 v[68:71], v[204:207], v[226:229], v[68:71]
	v_mfma_f32_16x16x32_bf16 v[64:67], v[208:211], v[226:229], v[64:67]
	s_waitcnt vmcnt(7)
	ds_write_b128 v152, v[128:131] offset:28672
	s_waitcnt lgkmcnt(7)
	v_mfma_f32_16x16x32_bf16 v[60:63], v[196:199], v[230:233], v[60:63]
	v_mfma_f32_16x16x32_bf16 v[56:59], v[200:203], v[230:233], v[56:59]
	v_mfma_f32_16x16x32_bf16 v[52:55], v[204:207], v[230:233], v[52:55]
	v_mfma_f32_16x16x32_bf16 v[48:51], v[208:211], v[230:233], v[48:51]
	s_waitcnt vmcnt(7)
	ds_write_b128 v152, v[116:119] offset:40960
	s_waitcnt lgkmcnt(7)
	v_mfma_f32_16x16x32_bf16 v[44:47], v[196:199], v[234:237], v[44:47]
	v_mfma_f32_16x16x32_bf16 v[40:43], v[200:203], v[234:237], v[40:43]
	v_mfma_f32_16x16x32_bf16 v[36:39], v[204:207], v[234:237], v[36:39]
	v_mfma_f32_16x16x32_bf16 v[32:35], v[208:211], v[234:237], v[32:35]
	s_waitcnt vmcnt(6)
	ds_write_b128 v152, v[132:135] offset:45056
	s_waitcnt lgkmcnt(7)
	v_mfma_f32_16x16x32_bf16 v[28:31], v[196:199], v[238:241], v[28:31]
	v_mfma_f32_16x16x32_bf16 v[24:27], v[200:203], v[238:241], v[24:27]
	v_mfma_f32_16x16x32_bf16 v[20:23], v[204:207], v[238:241], v[20:23]
	v_mfma_f32_16x16x32_bf16 v[16:19], v[208:211], v[238:241], v[16:19]
	s_waitcnt lgkmcnt(6)
	v_mfma_f32_16x16x32_bf16 v[12:15], v[196:199], v[242:245], v[12:15]
	v_mfma_f32_16x16x32_bf16 v[8:11], v[200:203], v[242:245], v[8:11]
	v_mfma_f32_16x16x32_bf16 v[4:7], v[204:207], v[242:245], v[4:7]
	v_mfma_f32_16x16x32_bf16 v[0:3], v[208:211], v[242:245], v[0:3]
	s_setprio 0
	s_min_u32 s10, s10, 0x380
	s_lshl_b32 s16, s10, 1
	s_mov_b32 s27, s17
	s_add_i32 s26, s16, 0xc0
	v_lshl_add_u64 v[112:113], v[154:155], 0, s[16:17]
	v_lshl_add_u64 v[116:117], v[156:157], 0, s[16:17]
	v_lshl_add_u64 v[120:121], v[158:159], 0, s[26:27]
	v_lshl_add_u64 v[124:125], v[160:161], 0, s[26:27]
	v_lshl_add_u64 v[128:129], v[162:163], 0, s[26:27]
	v_lshl_add_u64 v[132:133], v[164:165], 0, s[26:27]
	s_waitcnt lgkmcnt(0)
	s_barrier
	global_load_dwordx4 v[112:115], v[112:113], off offset:192
	ds_read_b128 v[196:199], v168 offset:40960
	global_load_dwordx4 v[116:119], v[116:117], off offset:192
	ds_read_b128 v[200:203], v168 offset:41984
	global_load_dwordx4 v[120:123], v[120:121], off
	ds_read_b128 v[204:207], v168 offset:43008
	global_load_dwordx4 v[124:127], v[124:125], off
	ds_read_b128 v[208:211], v168 offset:44032
	global_load_dwordx4 v[128:131], v[128:129], off
	ds_read_b128 v[212:215], v170
	global_load_dwordx4 v[132:135], v[132:133], off
	ds_read_b128 v[216:219], v170 offset:1024
	ds_read_b128 v[222:225], v170 offset:2048
	ds_read_b128 v[226:229], v170 offset:3072
	ds_read_b128 v[230:233], v170 offset:4096
	ds_read_b128 v[234:237], v170 offset:5120
	ds_read_b128 v[238:241], v170 offset:6144
	ds_read_b128 v[242:245], v170 offset:7168
	s_setprio 1
	s_waitcnt lgkmcnt(7)
	v_mfma_f32_16x16x32_bf16 v[148:151], v[196:199], v[212:215], v[148:151]
	v_mfma_f32_16x16x32_bf16 v[144:147], v[200:203], v[212:215], v[144:147]
	v_mfma_f32_16x16x32_bf16 v[140:143], v[204:207], v[212:215], v[140:143]
	v_mfma_f32_16x16x32_bf16 v[136:139], v[208:211], v[212:215], v[136:139]
	s_waitcnt vmcnt(11)
	ds_write_b128 v152, v[172:175]
	s_waitcnt lgkmcnt(7)
	v_mfma_f32_16x16x32_bf16 v[108:111], v[196:199], v[216:219], v[108:111]
	v_mfma_f32_16x16x32_bf16 v[104:107], v[200:203], v[216:219], v[104:107]
	v_mfma_f32_16x16x32_bf16 v[100:103], v[204:207], v[216:219], v[100:103]
	v_mfma_f32_16x16x32_bf16 v[96:99], v[208:211], v[216:219], v[96:99]
	s_waitcnt vmcnt(10)
	ds_write_b128 v152, v[176:179] offset:4096
	s_waitcnt lgkmcnt(7)
	v_mfma_f32_16x16x32_bf16 v[92:95], v[196:199], v[222:225], v[92:95]
	v_mfma_f32_16x16x32_bf16 v[88:91], v[200:203], v[222:225], v[88:91]
	v_mfma_f32_16x16x32_bf16 v[84:87], v[204:207], v[222:225], v[84:87]
	v_mfma_f32_16x16x32_bf16 v[80:83], v[208:211], v[222:225], v[80:83]
	s_waitcnt vmcnt(9)
	ds_write_b128 v152, v[180:183] offset:8192
	s_waitcnt lgkmcnt(7)
	v_mfma_f32_16x16x32_bf16 v[76:79], v[196:199], v[226:229], v[76:79]
	v_mfma_f32_16x16x32_bf16 v[72:75], v[200:203], v[226:229], v[72:75]
	v_mfma_f32_16x16x32_bf16 v[68:71], v[204:207], v[226:229], v[68:71]
	v_mfma_f32_16x16x32_bf16 v[64:67], v[208:211], v[226:229], v[64:67]
	s_waitcnt vmcnt(8)
	ds_write_b128 v152, v[184:187] offset:12288
	s_waitcnt lgkmcnt(7)
	v_mfma_f32_16x16x32_bf16 v[60:63], v[196:199], v[230:233], v[60:63]
	v_mfma_f32_16x16x32_bf16 v[56:59], v[200:203], v[230:233], v[56:59]
	v_mfma_f32_16x16x32_bf16 v[52:55], v[204:207], v[230:233], v[52:55]
	v_mfma_f32_16x16x32_bf16 v[48:51], v[208:211], v[230:233], v[48:51]
	s_waitcnt vmcnt(7)
	ds_write_b128 v152, v[188:191] offset:32768
	s_waitcnt lgkmcnt(7)
	v_mfma_f32_16x16x32_bf16 v[44:47], v[196:199], v[234:237], v[44:47]
	v_mfma_f32_16x16x32_bf16 v[40:43], v[200:203], v[234:237], v[40:43]
	v_mfma_f32_16x16x32_bf16 v[36:39], v[204:207], v[234:237], v[36:39]
	v_mfma_f32_16x16x32_bf16 v[32:35], v[208:211], v[234:237], v[32:35]
	s_waitcnt vmcnt(6)
	ds_write_b128 v152, v[192:195] offset:36864
	s_waitcnt lgkmcnt(7)
	v_mfma_f32_16x16x32_bf16 v[28:31], v[196:199], v[238:241], v[28:31]
	v_mfma_f32_16x16x32_bf16 v[24:27], v[200:203], v[238:241], v[24:27]
	v_mfma_f32_16x16x32_bf16 v[20:23], v[204:207], v[238:241], v[20:23]
	v_mfma_f32_16x16x32_bf16 v[16:19], v[208:211], v[238:241], v[16:19]
	s_waitcnt lgkmcnt(6)
	v_mfma_f32_16x16x32_bf16 v[12:15], v[196:199], v[242:245], v[12:15]
	v_mfma_f32_16x16x32_bf16 v[8:11], v[200:203], v[242:245], v[8:11]
	v_mfma_f32_16x16x32_bf16 v[4:7], v[204:207], v[242:245], v[4:7]
	v_mfma_f32_16x16x32_bf16 v[0:3], v[208:211], v[242:245], v[0:3]
	s_setprio 0
	s_add_i32 s1, s1, 2
	s_cmp_lt_u32 s1, 30
	s_mov_b32 s10, s11
	s_waitcnt lgkmcnt(0)
	s_barrier
	s_cbranch_scc1 .LBB0_706
	s_waitcnt vmcnt(4)
	v_mov_b32_e32 v116, v220
	s_nop 0
	v_and_b32_e32 v112, 0xffffff80, v116
	v_add_u32_e32 v117, s0, v112
	v_and_or_b32 v114, v116, 15, v117
	v_ashrrev_i32_e32 v115, 31, v114
	v_lshl_add_u64 v[112:113], v[114:115], 2, s[14:15]
	global_load_dword v246, v[112:113], off offset:64
	global_load_dword v247, v[112:113], off offset:128
	global_load_dword v248, v[112:113], off offset:192
	global_load_dword v249, v[112:113], off offset:256
	global_load_dword v250, v[112:113], off offset:320
	global_load_dword v251, v[112:113], off offset:384
	global_load_dword v252, v[112:113], off offset:448
	global_load_dword v122, v[112:113], off
	v_and_b32_e32 v112, 64, v116
	v_lshrrev_b32_e32 v115, 1, v116
	v_ashrrev_i32_e32 v116, 14, v117
	v_ashrrev_i32_e32 v117, 31, v116
	v_lshlrev_b32_e32 v152, 1, v112
	v_or_b32_e32 v118, 16, v114
	v_lshlrev_b64 v[116:117], 16, v[116:117]
	v_lshl_add_u64 v[112:113], s[38:39], 0, v[152:153]
	v_and_b32_e32 v152, 24, v115
	v_ashrrev_i32_e32 v119, 31, v118
	v_lshl_or_b32 v115, s12, 14, v116
	s_waitcnt vmcnt(4)
	v_lshl_add_u64 v[120:121], v[118:119], 2, s[14:15]
	v_lshl_add_u64 v[112:113], v[112:113], 0, v[152:153]
	s_waitcnt vmcnt(0)
	v_fmamk_f32 v116, v122, 0x3a800000, v166
	v_mul_f32_e32 v119, 0x4b800000, v116
	v_cmp_gt_f32_e32 vcc, s40, v116
	s_nop 1
	v_cndmask_b32_e32 v116, v116, v119, vcc
	v_rsq_f32_e32 v119, v116
	v_and_or_b32 v116, v114, s41, v115
	v_lshlrev_b64 v[122:123], 8, v[116:117]
	v_lshl_add_u64 v[122:123], v[112:113], 0, v[122:123]
	v_mul_f32_e32 v116, 0x45800000, v119
	v_cndmask_b32_e32 v116, v119, v116, vcc
	v_mul_f32_e32 v124, v149, v116
	v_mul_f32_e32 v125, v150, v116
	v_mul_f32_e32 v119, v148, v116
	v_mul_f32_e32 v126, v151, v116
	v_mul_f32_e32 v127, v144, v116
	v_mul_f32_e32 v128, v145, v116
	v_mul_f32_e32 v129, v146, v116
	v_mul_f32_e32 v130, v147, v116
	v_mul_f32_e32 v131, v140, v116
	v_cvt_pk_bf16_f32 v124, v119, v124
	v_cvt_pk_bf16_f32 v125, v125, v126
	v_mul_f32_e32 v132, v141, v116
	v_mul_f32_e32 v133, v142, v116
	v_mul_f32_e32 v134, v143, v116
	v_mul_f32_e32 v135, v136, v116
	v_mul_f32_e32 v136, v137, v116
	v_mul_f32_e32 v137, v138, v116
	v_mul_f32_e32 v116, v139, v116
	v_cvt_pk_bf16_f32 v126, v127, v128
	v_cvt_pk_bf16_f32 v127, v129, v130
	v_cvt_pk_bf16_f32 v128, v131, v132
	v_cvt_pk_bf16_f32 v129, v133, v134
	v_cvt_pk_bf16_f32 v130, v135, v136
	v_cvt_pk_bf16_f32 v131, v137, v116
	global_store_dwordx2 v[122:123], v[124:125], off
	global_store_dwordx2 v[122:123], v[126:127], off offset:32
	global_store_dwordx2 v[122:123], v[128:129], off offset:64
	global_store_dwordx2 v[122:123], v[130:131], off offset:96
	v_mov_b32_e32 v116, v246
	v_or_b32_e32 v120, 32, v114
	v_ashrrev_i32_e32 v121, 31, v120
	v_lshl_add_u64 v[122:123], v[120:121], 2, s[14:15]
	v_fmamk_f32 v116, v116, 0x3a800000, v166
	v_mul_f32_e32 v119, 0x4b800000, v116
	v_cmp_gt_f32_e32 vcc, s40, v116
	s_nop 1
	v_cndmask_b32_e32 v116, v116, v119, vcc
	v_rsq_f32_e32 v121, v116
	v_and_or_b32 v116, v118, s42, v115
	v_lshlrev_b64 v[118:119], 8, v[116:117]
	v_lshl_add_u64 v[118:119], v[112:113], 0, v[118:119]
	v_mul_f32_e32 v116, 0x45800000, v121
	v_cndmask_b32_e32 v116, v121, v116, vcc
	v_mul_f32_e32 v108, v108, v116
	v_mul_f32_e32 v109, v109, v116
	v_mul_f32_e32 v110, v110, v116
	v_mul_f32_e32 v111, v111, v116
	v_mul_f32_e32 v100, v100, v116
	v_mul_f32_e32 v101, v101, v116
	v_mul_f32_e32 v102, v102, v116
	v_mul_f32_e32 v103, v103, v116
	v_mul_f32_e32 v121, v96, v116
	v_mul_f32_e32 v124, v97, v116
	v_cvt_pk_bf16_f32 v96, v108, v109
	v_cvt_pk_bf16_f32 v97, v110, v111
	v_mul_f32_e32 v104, v104, v116
	v_mul_f32_e32 v105, v105, v116
	v_mul_f32_e32 v106, v106, v116
	v_mul_f32_e32 v107, v107, v116
	v_mul_f32_e32 v125, v98, v116
	v_mul_f32_e32 v116, v99, v116
	v_cvt_pk_bf16_f32 v98, v104, v105
	v_cvt_pk_bf16_f32 v99, v106, v107
	v_cvt_pk_bf16_f32 v100, v100, v101
	v_cvt_pk_bf16_f32 v101, v102, v103
	v_cvt_pk_bf16_f32 v102, v121, v124
	v_cvt_pk_bf16_f32 v103, v125, v116
	global_store_dwordx2 v[118:119], v[96:97], off
	global_store_dwordx2 v[118:119], v[98:99], off offset:32
	global_store_dwordx2 v[118:119], v[100:101], off offset:64
	global_store_dwordx2 v[118:119], v[102:103], off offset:96
	v_mov_b32_e32 v100, v247
	v_or_b32_e32 v96, 48, v114
	v_ashrrev_i32_e32 v97, 31, v96
	v_lshl_add_u64 v[98:99], v[96:97], 2, s[14:15]
	v_and_or_b32 v116, v120, s43, v115
	v_fmamk_f32 v97, v100, 0x3a800000, v166
	v_mul_f32_e32 v100, 0x4b800000, v97
	v_cmp_gt_f32_e32 vcc, s40, v97
	s_nop 1
	v_cndmask_b32_e32 v97, v97, v100, vcc
	v_rsq_f32_e32 v97, v97
	v_lshlrev_b64 v[100:101], 8, v[116:117]
	v_lshl_add_u64 v[100:101], v[112:113], 0, v[100:101]
	v_and_or_b32 v116, v96, s44, v115
	v_mul_f32_e32 v102, 0x45800000, v97
	v_cndmask_b32_e32 v97, v97, v102, vcc
	v_mul_f32_e32 v92, v92, v97
	v_mul_f32_e32 v93, v93, v97
	v_mul_f32_e32 v94, v94, v97
	v_mul_f32_e32 v95, v95, v97
	v_mul_f32_e32 v84, v84, v97
	v_mul_f32_e32 v85, v85, v97
	v_mul_f32_e32 v86, v86, v97
	v_mul_f32_e32 v87, v87, v97
	v_mul_f32_e32 v102, v80, v97
	v_mul_f32_e32 v103, v81, v97
	v_cvt_pk_bf16_f32 v80, v92, v93
	v_cvt_pk_bf16_f32 v81, v94, v95
	v_mul_f32_e32 v88, v88, v97
	v_mul_f32_e32 v89, v89, v97
	v_mul_f32_e32 v90, v90, v97
	v_mul_f32_e32 v91, v91, v97
	v_mul_f32_e32 v104, v82, v97
	v_mul_f32_e32 v97, v83, v97
	v_cvt_pk_bf16_f32 v82, v88, v89
	v_cvt_pk_bf16_f32 v83, v90, v91
	v_cvt_pk_bf16_f32 v84, v84, v85
	v_cvt_pk_bf16_f32 v85, v86, v87
	v_cvt_pk_bf16_f32 v86, v102, v103
	v_cvt_pk_bf16_f32 v87, v104, v97
	global_store_dwordx2 v[100:101], v[80:81], off
	global_store_dwordx2 v[100:101], v[82:83], off offset:32
	global_store_dwordx2 v[100:101], v[84:85], off offset:64
	global_store_dwordx2 v[100:101], v[86:87], off offset:96
	v_mov_b32_e32 v84, v248
	v_or_b32_e32 v80, 64, v114
	v_ashrrev_i32_e32 v81, 31, v80
	v_lshl_add_u64 v[82:83], v[80:81], 2, s[14:15]
	v_fmamk_f32 v81, v84, 0x3a800000, v166
	v_mul_f32_e32 v84, 0x4b800000, v81
	v_cmp_gt_f32_e32 vcc, s40, v81
	s_nop 1
	v_cndmask_b32_e32 v81, v81, v84, vcc
	v_rsq_f32_e32 v81, v81
	v_lshlrev_b64 v[84:85], 8, v[116:117]
	v_lshl_add_u64 v[84:85], v[112:113], 0, v[84:85]
	v_and_or_b32 v116, v80, s45, v115
	v_mul_f32_e32 v86, 0x45800000, v81
	v_cndmask_b32_e32 v81, v81, v86, vcc
	v_mul_f32_e32 v76, v76, v81
	v_mul_f32_e32 v77, v77, v81
	v_mul_f32_e32 v78, v78, v81
	v_mul_f32_e32 v79, v79, v81
	v_mul_f32_e32 v68, v68, v81
	v_mul_f32_e32 v69, v69, v81
	v_mul_f32_e32 v70, v70, v81
	v_mul_f32_e32 v71, v71, v81
	v_mul_f32_e32 v86, v64, v81
	v_mul_f32_e32 v87, v65, v81
	v_cvt_pk_bf16_f32 v64, v76, v77
	v_cvt_pk_bf16_f32 v65, v78, v79
	v_mul_f32_e32 v72, v72, v81
	v_mul_f32_e32 v73, v73, v81
	v_mul_f32_e32 v74, v74, v81
	v_mul_f32_e32 v75, v75, v81
	v_mul_f32_e32 v88, v66, v81
	v_mul_f32_e32 v81, v67, v81
	v_cvt_pk_bf16_f32 v66, v72, v73
	v_cvt_pk_bf16_f32 v67, v74, v75
	v_cvt_pk_bf16_f32 v68, v68, v69
	v_cvt_pk_bf16_f32 v69, v70, v71
	v_cvt_pk_bf16_f32 v70, v86, v87
	v_cvt_pk_bf16_f32 v71, v88, v81
	global_store_dwordx2 v[84:85], v[64:65], off
	global_store_dwordx2 v[84:85], v[66:67], off offset:32
	global_store_dwordx2 v[84:85], v[68:69], off offset:64
	global_store_dwordx2 v[84:85], v[70:71], off offset:96
	v_mov_b32_e32 v68, v249
	v_or_b32_e32 v64, 0x50, v114
	v_ashrrev_i32_e32 v65, 31, v64
	v_lshl_add_u64 v[66:67], v[64:65], 2, s[14:15]
	v_fmamk_f32 v65, v68, 0x3a800000, v166
	v_mul_f32_e32 v68, 0x4b800000, v65
	v_cmp_gt_f32_e32 vcc, s40, v65
	s_nop 1
	v_cndmask_b32_e32 v65, v65, v68, vcc
	v_rsq_f32_e32 v65, v65
	v_lshlrev_b64 v[68:69], 8, v[116:117]
	v_lshl_add_u64 v[68:69], v[112:113], 0, v[68:69]
	v_and_or_b32 v116, v64, s46, v115
	v_mul_f32_e32 v70, 0x45800000, v65
	v_cndmask_b32_e32 v65, v65, v70, vcc
	v_mul_f32_e32 v60, v60, v65
	v_mul_f32_e32 v61, v61, v65
	v_mul_f32_e32 v62, v62, v65
	v_mul_f32_e32 v63, v63, v65
	v_mul_f32_e32 v52, v52, v65
	v_mul_f32_e32 v53, v53, v65
	v_mul_f32_e32 v54, v54, v65
	v_mul_f32_e32 v55, v55, v65
	v_mul_f32_e32 v70, v48, v65
	v_mul_f32_e32 v71, v49, v65
	v_cvt_pk_bf16_f32 v48, v60, v61
	v_cvt_pk_bf16_f32 v49, v62, v63
	v_mul_f32_e32 v56, v56, v65
	v_mul_f32_e32 v57, v57, v65
	v_mul_f32_e32 v58, v58, v65
	v_mul_f32_e32 v59, v59, v65
	v_mul_f32_e32 v72, v50, v65
	v_mul_f32_e32 v65, v51, v65
	v_cvt_pk_bf16_f32 v50, v56, v57
	v_cvt_pk_bf16_f32 v51, v58, v59
	v_cvt_pk_bf16_f32 v52, v52, v53
	v_cvt_pk_bf16_f32 v53, v54, v55
	v_cvt_pk_bf16_f32 v54, v70, v71
	v_cvt_pk_bf16_f32 v55, v72, v65
	global_store_dwordx2 v[68:69], v[48:49], off
	global_store_dwordx2 v[68:69], v[50:51], off offset:32
	global_store_dwordx2 v[68:69], v[52:53], off offset:64
	global_store_dwordx2 v[68:69], v[54:55], off offset:96
	v_mov_b32_e32 v52, v250
	v_or_b32_e32 v48, 0x60, v114
	v_ashrrev_i32_e32 v49, 31, v48
	v_lshl_add_u64 v[50:51], v[48:49], 2, s[14:15]
	v_fmamk_f32 v49, v52, 0x3a800000, v166
	v_mul_f32_e32 v52, 0x4b800000, v49
	v_cmp_gt_f32_e32 vcc, s40, v49
	s_nop 1
	v_cndmask_b32_e32 v49, v49, v52, vcc
	v_rsq_f32_e32 v49, v49
	v_lshlrev_b64 v[52:53], 8, v[116:117]
	v_lshl_add_u64 v[52:53], v[112:113], 0, v[52:53]
	v_and_or_b32 v116, v48, s47, v115
	v_mul_f32_e32 v54, 0x45800000, v49
	v_cndmask_b32_e32 v49, v49, v54, vcc
	v_mul_f32_e32 v44, v44, v49
	v_mul_f32_e32 v45, v45, v49
	v_mul_f32_e32 v46, v46, v49
	v_mul_f32_e32 v47, v47, v49
	v_mul_f32_e32 v36, v36, v49
	v_mul_f32_e32 v37, v37, v49
	v_mul_f32_e32 v38, v38, v49
	v_mul_f32_e32 v39, v39, v49
	v_mul_f32_e32 v54, v32, v49
	v_mul_f32_e32 v55, v33, v49
	v_cvt_pk_bf16_f32 v32, v44, v45
	v_cvt_pk_bf16_f32 v33, v46, v47
	v_mul_f32_e32 v40, v40, v49
	v_mul_f32_e32 v41, v41, v49
	v_mul_f32_e32 v42, v42, v49
	v_mul_f32_e32 v43, v43, v49
	v_mul_f32_e32 v56, v34, v49
	v_mul_f32_e32 v49, v35, v49
	v_cvt_pk_bf16_f32 v34, v40, v41
	v_cvt_pk_bf16_f32 v35, v42, v43
	v_cvt_pk_bf16_f32 v36, v36, v37
	v_cvt_pk_bf16_f32 v37, v38, v39
	v_cvt_pk_bf16_f32 v38, v54, v55
	v_cvt_pk_bf16_f32 v39, v56, v49
	global_store_dwordx2 v[52:53], v[32:33], off
	global_store_dwordx2 v[52:53], v[34:35], off offset:32
	global_store_dwordx2 v[52:53], v[36:37], off offset:64
	global_store_dwordx2 v[52:53], v[38:39], off offset:96
	v_mov_b32_e32 v36, v251
	v_or_b32_e32 v32, 0x70, v114
	v_ashrrev_i32_e32 v33, 31, v32
	v_lshl_add_u64 v[34:35], v[32:33], 2, s[14:15]
	v_fmamk_f32 v33, v36, 0x3a800000, v166
	v_mul_f32_e32 v36, 0x4b800000, v33
	v_cmp_gt_f32_e32 vcc, s40, v33
	s_nop 1
	v_cndmask_b32_e32 v33, v33, v36, vcc
	v_rsq_f32_e32 v33, v33
	v_lshlrev_b64 v[36:37], 8, v[116:117]
	v_lshl_add_u64 v[36:37], v[112:113], 0, v[36:37]
	v_and_or_b32 v116, v32, s48, v115
	v_mul_f32_e32 v38, 0x45800000, v33
	v_cndmask_b32_e32 v33, v33, v38, vcc
	v_mul_f32_e32 v28, v28, v33
	v_mul_f32_e32 v29, v29, v33
	v_mul_f32_e32 v30, v30, v33
	v_mul_f32_e32 v31, v31, v33
	v_mul_f32_e32 v20, v20, v33
	v_mul_f32_e32 v21, v21, v33
	v_mul_f32_e32 v22, v22, v33
	v_mul_f32_e32 v23, v23, v33
	v_mul_f32_e32 v38, v16, v33
	v_mul_f32_e32 v39, v17, v33
	v_cvt_pk_bf16_f32 v16, v28, v29
	v_cvt_pk_bf16_f32 v17, v30, v31
	v_mul_f32_e32 v24, v24, v33
	v_mul_f32_e32 v25, v25, v33
	v_mul_f32_e32 v26, v26, v33
	v_mul_f32_e32 v27, v27, v33
	v_mul_f32_e32 v40, v18, v33
	v_mul_f32_e32 v33, v19, v33
	v_cvt_pk_bf16_f32 v18, v24, v25
	v_cvt_pk_bf16_f32 v19, v26, v27
	v_cvt_pk_bf16_f32 v20, v20, v21
	v_cvt_pk_bf16_f32 v21, v22, v23
	v_cvt_pk_bf16_f32 v22, v38, v39
	v_cvt_pk_bf16_f32 v23, v40, v33
	global_store_dwordx2 v[36:37], v[16:17], off
	global_store_dwordx2 v[36:37], v[18:19], off offset:32
	global_store_dwordx2 v[36:37], v[20:21], off offset:64
	global_store_dwordx2 v[36:37], v[22:23], off offset:96
	v_mov_b32_e32 v16, v252
	v_fmamk_f32 v16, v16, 0x3a800000, v166
	v_mul_f32_e32 v17, 0x4b800000, v16
	v_cmp_gt_f32_e32 vcc, s40, v16
	s_nop 1
	v_cndmask_b32_e32 v16, v16, v17, vcc
	v_rsq_f32_e32 v18, v16
	v_lshlrev_b64 v[16:17], 8, v[116:117]
	v_lshl_add_u64 v[16:17], v[112:113], 0, v[16:17]
	v_mul_f32_e32 v19, 0x45800000, v18
	v_cndmask_b32_e32 v18, v18, v19, vcc
	v_mul_f32_e32 v12, v12, v18
	v_mul_f32_e32 v13, v13, v18
	v_mul_f32_e32 v14, v14, v18
	v_mul_f32_e32 v15, v15, v18
	v_mul_f32_e32 v4, v4, v18
	v_mul_f32_e32 v5, v5, v18
	v_mul_f32_e32 v6, v6, v18
	v_mul_f32_e32 v7, v7, v18
	v_mul_f32_e32 v19, v0, v18
	v_mul_f32_e32 v20, v1, v18
	v_cvt_pk_bf16_f32 v0, v12, v13
	v_cvt_pk_bf16_f32 v1, v14, v15
	v_mul_f32_e32 v8, v8, v18
	v_mul_f32_e32 v9, v9, v18
	v_mul_f32_e32 v10, v10, v18
	v_mul_f32_e32 v11, v11, v18
	v_mul_f32_e32 v21, v2, v18
	v_mul_f32_e32 v18, v3, v18
	v_cvt_pk_bf16_f32 v2, v8, v9
	v_cvt_pk_bf16_f32 v3, v10, v11
	v_cvt_pk_bf16_f32 v4, v4, v5
	v_cvt_pk_bf16_f32 v5, v6, v7
	v_cvt_pk_bf16_f32 v6, v19, v20
	v_cvt_pk_bf16_f32 v7, v21, v18
	global_store_dwordx2 v[16:17], v[0:1], off
	global_store_dwordx2 v[16:17], v[2:3], off offset:32
	global_store_dwordx2 v[16:17], v[4:5], off offset:64
	global_store_dwordx2 v[16:17], v[6:7], off offset:96
	s_branch .LBB0_699

.LBB0_769:
	s_add_i32 s14, s13, 64
	s_min_u32 s15, s14, 0x3e0
	s_lshl_b32 s34, s15, 1
	v_lshl_add_u64 v[172:173], v[154:155], 0, s[34:35]
	v_lshl_add_u64 v[176:177], v[158:159], 0, s[34:35]
	v_lshl_add_u64 v[180:181], v[160:161], 0, s[34:35]
	v_lshl_add_u64 v[184:185], v[162:163], 0, s[34:35]
	v_lshl_add_u64 v[188:189], v[156:157], 0, s[34:35]
	v_lshl_add_u64 v[192:193], v[164:165], 0, s[34:35]
	global_load_dwordx4 v[172:175], v[172:173], off
	ds_read_b128 v[196:199], v171 offset:32768
	global_load_dwordx4 v[176:179], v[176:177], off
	ds_read_b128 v[200:203], v171 offset:33792
	global_load_dwordx4 v[180:183], v[180:181], off
	ds_read_b128 v[204:207], v171 offset:34816
	global_load_dwordx4 v[184:187], v[184:185], off
	ds_read_b128 v[208:211], v171 offset:35840
	global_load_dwordx4 v[188:191], v[188:189], off
	ds_read_b128 v[212:215], v169
	global_load_dwordx4 v[192:195], v[192:193], off
	ds_read_b128 v[216:219], v169 offset:1024
	ds_read_b128 v[222:225], v169 offset:2048
	ds_read_b128 v[226:229], v169 offset:3072
	ds_read_b128 v[230:233], v169 offset:4096
	ds_read_b128 v[234:237], v169 offset:5120
	ds_read_b128 v[238:241], v169 offset:6144
	ds_read_b128 v[242:245], v169 offset:7168
	s_setprio 1
	s_waitcnt lgkmcnt(7)
	v_mfma_f32_16x16x32_bf16 v[148:151], v[196:199], v[212:215], v[148:151]
	v_mfma_f32_16x16x32_bf16 v[144:147], v[200:203], v[212:215], v[144:147]
	v_mfma_f32_16x16x32_bf16 v[116:119], v[204:207], v[212:215], v[116:119]
	v_mfma_f32_16x16x32_bf16 v[112:115], v[208:211], v[212:215], v[112:115]
	s_waitcnt vmcnt(11)
	ds_write_b128 v152, v[120:123] offset:16384
	s_waitcnt lgkmcnt(7)
	v_mfma_f32_16x16x32_bf16 v[108:111], v[196:199], v[216:219], v[108:111]
	v_mfma_f32_16x16x32_bf16 v[104:107], v[200:203], v[216:219], v[104:107]
	v_mfma_f32_16x16x32_bf16 v[100:103], v[204:207], v[216:219], v[100:103]
	v_mfma_f32_16x16x32_bf16 v[96:99], v[208:211], v[216:219], v[96:99]
	s_waitcnt vmcnt(9)
	ds_write_b128 v152, v[128:131] offset:20480
	s_waitcnt lgkmcnt(7)
	v_mfma_f32_16x16x32_bf16 v[92:95], v[196:199], v[222:225], v[92:95]
	v_mfma_f32_16x16x32_bf16 v[88:91], v[200:203], v[222:225], v[88:91]
	v_mfma_f32_16x16x32_bf16 v[84:87], v[204:207], v[222:225], v[84:87]
	v_mfma_f32_16x16x32_bf16 v[80:83], v[208:211], v[222:225], v[80:83]
	s_waitcnt vmcnt(8)
	ds_write_b128 v152, v[132:135] offset:24576
	s_waitcnt lgkmcnt(7)
	v_mfma_f32_16x16x32_bf16 v[76:79], v[196:199], v[226:229], v[76:79]
	v_mfma_f32_16x16x32_bf16 v[72:75], v[200:203], v[226:229], v[72:75]
	v_mfma_f32_16x16x32_bf16 v[68:71], v[204:207], v[226:229], v[68:71]
	v_mfma_f32_16x16x32_bf16 v[64:67], v[208:211], v[226:229], v[64:67]
	s_waitcnt vmcnt(7)
	ds_write_b128 v152, v[136:139] offset:28672
	s_waitcnt lgkmcnt(7)
	v_mfma_f32_16x16x32_bf16 v[60:63], v[196:199], v[230:233], v[60:63]
	v_mfma_f32_16x16x32_bf16 v[56:59], v[200:203], v[230:233], v[56:59]
	v_mfma_f32_16x16x32_bf16 v[52:55], v[204:207], v[230:233], v[52:55]
	v_mfma_f32_16x16x32_bf16 v[48:51], v[208:211], v[230:233], v[48:51]
	s_waitcnt vmcnt(7)
	ds_write_b128 v152, v[124:127] offset:40960
	s_waitcnt lgkmcnt(7)
	v_mfma_f32_16x16x32_bf16 v[44:47], v[196:199], v[234:237], v[44:47]
	v_mfma_f32_16x16x32_bf16 v[40:43], v[200:203], v[234:237], v[40:43]
	v_mfma_f32_16x16x32_bf16 v[36:39], v[204:207], v[234:237], v[36:39]
	v_mfma_f32_16x16x32_bf16 v[32:35], v[208:211], v[234:237], v[32:35]
	s_waitcnt vmcnt(6)
	ds_write_b128 v152, v[140:143] offset:45056
	s_waitcnt lgkmcnt(7)
	v_mfma_f32_16x16x32_bf16 v[28:31], v[196:199], v[238:241], v[28:31]
	v_mfma_f32_16x16x32_bf16 v[24:27], v[200:203], v[238:241], v[24:27]
	v_mfma_f32_16x16x32_bf16 v[20:23], v[204:207], v[238:241], v[20:23]
	v_mfma_f32_16x16x32_bf16 v[16:19], v[208:211], v[238:241], v[16:19]
	s_waitcnt lgkmcnt(6)
	v_mfma_f32_16x16x32_bf16 v[12:15], v[196:199], v[242:245], v[12:15]
	v_mfma_f32_16x16x32_bf16 v[8:11], v[200:203], v[242:245], v[8:11]
	v_mfma_f32_16x16x32_bf16 v[4:7], v[204:207], v[242:245], v[4:7]
	v_mfma_f32_16x16x32_bf16 v[0:3], v[208:211], v[242:245], v[0:3]
	s_setprio 0
	s_min_u32 s13, s13, 0x380
	s_lshl_b32 s34, s13, 1
	s_mov_b32 s17, s35
	s_add_i32 s16, s34, 0xc0
	v_lshl_add_u64 v[120:121], v[154:155], 0, s[34:35]
	v_lshl_add_u64 v[124:125], v[156:157], 0, s[34:35]
	v_lshl_add_u64 v[128:129], v[158:159], 0, s[16:17]
	v_lshl_add_u64 v[132:133], v[160:161], 0, s[16:17]
	v_lshl_add_u64 v[136:137], v[162:163], 0, s[16:17]
	v_lshl_add_u64 v[140:141], v[164:165], 0, s[16:17]
	s_waitcnt lgkmcnt(0)
	s_barrier
	global_load_dwordx4 v[120:123], v[120:121], off offset:192
	ds_read_b128 v[196:199], v168 offset:40960
	global_load_dwordx4 v[124:127], v[124:125], off offset:192
	ds_read_b128 v[200:203], v168 offset:41984
	global_load_dwordx4 v[128:131], v[128:129], off
	ds_read_b128 v[204:207], v168 offset:43008
	global_load_dwordx4 v[132:135], v[132:133], off
	ds_read_b128 v[208:211], v168 offset:44032
	global_load_dwordx4 v[136:139], v[136:137], off
	ds_read_b128 v[212:215], v170
	global_load_dwordx4 v[140:143], v[140:141], off
	ds_read_b128 v[216:219], v170 offset:1024
	ds_read_b128 v[222:225], v170 offset:2048
	ds_read_b128 v[226:229], v170 offset:3072
	ds_read_b128 v[230:233], v170 offset:4096
	ds_read_b128 v[234:237], v170 offset:5120
	ds_read_b128 v[238:241], v170 offset:6144
	ds_read_b128 v[242:245], v170 offset:7168
	s_setprio 1
	s_waitcnt lgkmcnt(7)
	v_mfma_f32_16x16x32_bf16 v[148:151], v[196:199], v[212:215], v[148:151]
	v_mfma_f32_16x16x32_bf16 v[144:147], v[200:203], v[212:215], v[144:147]
	v_mfma_f32_16x16x32_bf16 v[116:119], v[204:207], v[212:215], v[116:119]
	v_mfma_f32_16x16x32_bf16 v[112:115], v[208:211], v[212:215], v[112:115]
	s_waitcnt vmcnt(11)
	ds_write_b128 v152, v[172:175]
	s_waitcnt lgkmcnt(7)
	v_mfma_f32_16x16x32_bf16 v[108:111], v[196:199], v[216:219], v[108:111]
	v_mfma_f32_16x16x32_bf16 v[104:107], v[200:203], v[216:219], v[104:107]
	v_mfma_f32_16x16x32_bf16 v[100:103], v[204:207], v[216:219], v[100:103]
	v_mfma_f32_16x16x32_bf16 v[96:99], v[208:211], v[216:219], v[96:99]
	s_waitcnt vmcnt(10)
	ds_write_b128 v152, v[176:179] offset:4096
	s_waitcnt lgkmcnt(7)
	v_mfma_f32_16x16x32_bf16 v[92:95], v[196:199], v[222:225], v[92:95]
	v_mfma_f32_16x16x32_bf16 v[88:91], v[200:203], v[222:225], v[88:91]
	v_mfma_f32_16x16x32_bf16 v[84:87], v[204:207], v[222:225], v[84:87]
	v_mfma_f32_16x16x32_bf16 v[80:83], v[208:211], v[222:225], v[80:83]
	s_waitcnt vmcnt(9)
	ds_write_b128 v152, v[180:183] offset:8192
	s_waitcnt lgkmcnt(7)
	v_mfma_f32_16x16x32_bf16 v[76:79], v[196:199], v[226:229], v[76:79]
	v_mfma_f32_16x16x32_bf16 v[72:75], v[200:203], v[226:229], v[72:75]
	v_mfma_f32_16x16x32_bf16 v[68:71], v[204:207], v[226:229], v[68:71]
	v_mfma_f32_16x16x32_bf16 v[64:67], v[208:211], v[226:229], v[64:67]
	s_waitcnt vmcnt(8)
	ds_write_b128 v152, v[184:187] offset:12288
	s_waitcnt lgkmcnt(7)
	v_mfma_f32_16x16x32_bf16 v[60:63], v[196:199], v[230:233], v[60:63]
	v_mfma_f32_16x16x32_bf16 v[56:59], v[200:203], v[230:233], v[56:59]
	v_mfma_f32_16x16x32_bf16 v[52:55], v[204:207], v[230:233], v[52:55]
	v_mfma_f32_16x16x32_bf16 v[48:51], v[208:211], v[230:233], v[48:51]
	s_waitcnt vmcnt(7)
	ds_write_b128 v152, v[188:191] offset:32768
	s_waitcnt lgkmcnt(7)
	v_mfma_f32_16x16x32_bf16 v[44:47], v[196:199], v[234:237], v[44:47]
	v_mfma_f32_16x16x32_bf16 v[40:43], v[200:203], v[234:237], v[40:43]
	v_mfma_f32_16x16x32_bf16 v[36:39], v[204:207], v[234:237], v[36:39]
	v_mfma_f32_16x16x32_bf16 v[32:35], v[208:211], v[234:237], v[32:35]
	s_waitcnt vmcnt(6)
	ds_write_b128 v152, v[192:195] offset:36864
	s_waitcnt lgkmcnt(7)
	v_mfma_f32_16x16x32_bf16 v[28:31], v[196:199], v[238:241], v[28:31]
	v_mfma_f32_16x16x32_bf16 v[24:27], v[200:203], v[238:241], v[24:27]
	v_mfma_f32_16x16x32_bf16 v[20:23], v[204:207], v[238:241], v[20:23]
	v_mfma_f32_16x16x32_bf16 v[16:19], v[208:211], v[238:241], v[16:19]
	s_waitcnt lgkmcnt(6)
	v_mfma_f32_16x16x32_bf16 v[12:15], v[196:199], v[242:245], v[12:15]
	v_mfma_f32_16x16x32_bf16 v[8:11], v[200:203], v[242:245], v[8:11]
	v_mfma_f32_16x16x32_bf16 v[4:7], v[204:207], v[242:245], v[4:7]
	v_mfma_f32_16x16x32_bf16 v[0:3], v[208:211], v[242:245], v[0:3]
	s_setprio 0
	s_add_i32 s11, s11, 2
	s_cmp_lt_u32 s11, 30
	s_mov_b32 s13, s14
	s_waitcnt lgkmcnt(0)
	s_barrier
	s_cbranch_scc1 .LBB0_769
	s_waitcnt vmcnt(4)
	v_mov_b32_e32 v126, v220
	v_mov_b64_e32 v[124:125], s[72:73]
	v_and_b32_e32 v120, 0xffffff80, v126
	v_add_u32_e32 v120, s12, v120
	v_and_or_b32 v122, v126, 15, v120
	v_ashrrev_i32_e32 v123, 31, v122
	v_lshl_add_u64 v[120:121], v[122:123], 2, s[0:1]
	global_load_dword v246, v[120:121], off offset:64
	global_load_dword v247, v[120:121], off offset:128
	global_load_dword v248, v[120:121], off offset:192
	global_load_dword v249, v[120:121], off offset:256
	global_load_dword v250, v[120:121], off offset:320
	global_load_dword v251, v[120:121], off offset:384
	global_load_dword v252, v[120:121], off offset:448
	global_load_dword v120, v[120:121], off
	v_and_b32_e32 v121, 64, v126
	v_lshrrev_b32_e32 v126, 2, v126
	v_and_b32_e32 v126, 12, v126
	s_waitcnt vmcnt(0)
	v_fmamk_f32 v120, v120, 0x3a800000, v167
	v_mul_f32_e32 v127, 0x4b800000, v120
	v_cmp_gt_f32_e32 vcc, s42, v120
	s_nop 1
	v_cndmask_b32_e32 v120, v120, v127, vcc
	v_rsq_f32_e32 v127, v120
	v_or3_b32 v120, v121, v126, s10
	v_mad_i64_i32 v[124:125], s[10:11], v122, s41, v[124:125]
	v_mul_f32_e32 v121, 0x45800000, v127
	v_cndmask_b32_e32 v129, v127, v121, vcc
	v_mul_f32_e32 v132, v148, v129
	v_mul_f32_e32 v131, v149, v129
	v_mul_f32_e32 v130, v150, v129
	v_mul_f32_e32 v128, v151, v129
	v_cmp_lt_i32_e64 s[10:11], s43, v120
	s_and_saveexec_b64 s[12:13], s[10:11]
	s_xor_b64 s[12:13], exec, s[12:13]
	s_cbranch_execz .LBB0_774
	v_cmp_gt_u32_e32 vcc, s44, v120
	s_and_saveexec_b64 s[14:15], vcc
	s_cbranch_execz .LBB0_773
	v_mul_f32_e32 v121, 0xbfb8aa3b, v132
	v_exp_f32_e32 v121, v121
	v_mul_f32_e32 v126, 0xbfb8aa3b, v131
	v_mul_f32_e32 v127, 0xbfb8aa3b, v128
	v_exp_f32_e32 v126, v126
	v_add_f32_e32 v121, 1.0, v121
	v_rcp_f32_e32 v132, v121
	v_mul_f32_e32 v121, 0xbfb8aa3b, v130
	v_exp_f32_e32 v121, v121
	v_exp_f32_e32 v127, v127
	v_add_f32_e32 v126, 1.0, v126
	v_rcp_f32_e32 v133, v126
	v_add_f32_e32 v121, 1.0, v121
	v_rcp_f32_e32 v134, v121
	v_add_f32_e32 v121, 1.0, v127
	v_rcp_f32_e32 v135, v121
	v_mov_b32_e32 v121, v153
	v_lshl_add_u64 v[126:127], v[120:121], 2, v[124:125]
	v_add_co_u32_e32 v126, vcc, 0x2ffe000, v126
	s_nop 1
	v_addc_co_u32_e32 v127, vcc, 0, v127, vcc
	global_store_dwordx4 v[126:127], v[132:135], off

.LBB0_794:
	s_or_b64 exec, exec, s[26:27]
	v_or_b32_e32 v114, 16, v122
	v_ashrrev_i32_e32 v115, 31, v114
	v_lshl_add_u64 v[112:113], v[114:115], 2, s[0:1]
	v_mov_b32_e32 v112, v246
	v_fmamk_f32 v112, v112, 0x3a800000, v167
	v_mul_f32_e32 v113, 0x4b800000, v112
	v_cmp_gt_f32_e32 vcc, s42, v112
	s_nop 1
	v_cndmask_b32_e32 v112, v112, v113, vcc
	v_rsq_f32_e32 v117, v112
	v_mov_b64_e32 v[112:113], s[72:73]
	v_mad_i64_i32 v[112:113], s[26:27], v114, s41, v[112:113]
	v_mul_f32_e32 v118, 0x45800000, v117
	v_cndmask_b32_e32 v117, v117, v118, vcc
	v_mul_f32_e32 v124, v108, v117
	v_mul_f32_e32 v119, v109, v117
	v_mul_f32_e32 v118, v110, v117
	v_mul_f32_e32 v110, v111, v117
	s_and_saveexec_b64 s[26:27], s[10:11]
	s_xor_b64 s[26:27], exec, s[26:27]
	s_cbranch_execz .LBB0_798
	v_cmp_gt_u32_e32 vcc, s44, v120
	s_and_saveexec_b64 s[36:37], vcc
	s_cbranch_execz .LBB0_797
	v_mul_f32_e32 v108, 0xbfb8aa3b, v124
	v_mul_f32_e32 v109, 0xbfb8aa3b, v119
	v_mul_f32_e32 v111, 0xbfb8aa3b, v118
	v_mul_f32_e32 v110, 0xbfb8aa3b, v110
	v_exp_f32_e32 v108, v108
	v_exp_f32_e32 v109, v109
	v_exp_f32_e32 v111, v111
	v_exp_f32_e32 v118, v110
	v_add_f32_e32 v108, 1.0, v108
	v_add_f32_e32 v109, 1.0, v109
	v_add_f32_e32 v110, 1.0, v111
	v_add_f32_e32 v111, 1.0, v118
	v_rcp_f32_e32 v108, v108
	v_rcp_f32_e32 v109, v109
	v_rcp_f32_e32 v110, v110
	v_rcp_f32_e32 v111, v111
	v_mov_b32_e32 v152, v120
	v_lshl_add_u64 v[118:119], v[152:153], 2, v[112:113]
	v_add_co_u32_e32 v118, vcc, 0x2ffe000, v118
	s_nop 1
	v_addc_co_u32_e32 v119, vcc, 0, v119, vcc
	global_store_dwordx4 v[118:119], v[108:111], off

.LBB0_818:
	s_or_b64 exec, exec, s[26:27]
	v_or_b32_e32 v98, 32, v122
	v_ashrrev_i32_e32 v99, 31, v98
	v_lshl_add_u64 v[96:97], v[98:99], 2, s[0:1]
	v_mov_b32_e32 v96, v247
	v_fmamk_f32 v96, v96, 0x3a800000, v167
	v_mul_f32_e32 v97, 0x4b800000, v96
	v_cmp_gt_f32_e32 vcc, s42, v96
	s_nop 1
	v_cndmask_b32_e32 v96, v96, v97, vcc
	v_rsq_f32_e32 v100, v96
	v_mov_b64_e32 v[96:97], s[72:73]
	v_mad_i64_i32 v[96:97], s[26:27], v98, s41, v[96:97]
	v_mul_f32_e32 v101, 0x45800000, v100
	v_cndmask_b32_e32 v100, v100, v101, vcc
	v_mul_f32_e32 v103, v92, v100
	v_mul_f32_e32 v102, v93, v100
	v_mul_f32_e32 v101, v94, v100
	v_mul_f32_e32 v94, v95, v100
	s_and_saveexec_b64 s[26:27], s[10:11]
	s_xor_b64 s[26:27], exec, s[26:27]
	s_cbranch_execz .LBB0_822
	v_cmp_gt_u32_e32 vcc, s44, v120
	s_and_saveexec_b64 s[36:37], vcc
	s_cbranch_execz .LBB0_821
	v_mul_f32_e32 v92, 0xbfb8aa3b, v103
	v_mul_f32_e32 v93, 0xbfb8aa3b, v102
	v_mul_f32_e32 v95, 0xbfb8aa3b, v101
	v_mul_f32_e32 v94, 0xbfb8aa3b, v94
	v_exp_f32_e32 v92, v92
	v_exp_f32_e32 v93, v93
	v_exp_f32_e32 v95, v95
	v_exp_f32_e32 v101, v94
	v_add_f32_e32 v92, 1.0, v92
	v_add_f32_e32 v93, 1.0, v93
	v_add_f32_e32 v94, 1.0, v95
	v_add_f32_e32 v95, 1.0, v101
	v_rcp_f32_e32 v92, v92
	v_rcp_f32_e32 v93, v93
	v_rcp_f32_e32 v94, v94
	v_rcp_f32_e32 v95, v95
	v_mov_b32_e32 v152, v120
	v_lshl_add_u64 v[102:103], v[152:153], 2, v[96:97]
	v_add_co_u32_e32 v102, vcc, 0x2ffe000, v102
	s_nop 1
	v_addc_co_u32_e32 v103, vcc, 0, v103, vcc
	global_store_dwordx4 v[102:103], v[92:95], off

.LBB0_842:
	s_or_b64 exec, exec, s[26:27]
	v_or_b32_e32 v82, 48, v122
	v_ashrrev_i32_e32 v83, 31, v82
	v_lshl_add_u64 v[80:81], v[82:83], 2, s[0:1]
	v_mov_b32_e32 v80, v248
	v_fmamk_f32 v80, v80, 0x3a800000, v167
	v_mul_f32_e32 v81, 0x4b800000, v80
	v_cmp_gt_f32_e32 vcc, s42, v80
	s_nop 1
	v_cndmask_b32_e32 v80, v80, v81, vcc
	v_rsq_f32_e32 v84, v80
	v_mov_b64_e32 v[80:81], s[72:73]
	v_mad_i64_i32 v[80:81], s[26:27], v82, s41, v[80:81]
	v_mul_f32_e32 v85, 0x45800000, v84
	v_cndmask_b32_e32 v84, v84, v85, vcc
	v_mul_f32_e32 v87, v76, v84
	v_mul_f32_e32 v86, v77, v84
	v_mul_f32_e32 v85, v78, v84
	v_mul_f32_e32 v78, v79, v84
	s_and_saveexec_b64 s[26:27], s[10:11]
	s_xor_b64 s[26:27], exec, s[26:27]
	s_cbranch_execz .LBB0_846
	v_cmp_gt_u32_e32 vcc, s44, v120
	s_and_saveexec_b64 s[36:37], vcc
	s_cbranch_execz .LBB0_845
	v_mul_f32_e32 v76, 0xbfb8aa3b, v87
	v_mul_f32_e32 v77, 0xbfb8aa3b, v86
	v_mul_f32_e32 v79, 0xbfb8aa3b, v85
	v_mul_f32_e32 v78, 0xbfb8aa3b, v78
	v_exp_f32_e32 v76, v76
	v_exp_f32_e32 v77, v77
	v_exp_f32_e32 v79, v79
	v_exp_f32_e32 v85, v78
	v_add_f32_e32 v76, 1.0, v76
	v_add_f32_e32 v77, 1.0, v77
	v_add_f32_e32 v78, 1.0, v79
	v_add_f32_e32 v79, 1.0, v85
	v_rcp_f32_e32 v76, v76
	v_rcp_f32_e32 v77, v77
	v_rcp_f32_e32 v78, v78
	v_rcp_f32_e32 v79, v79
	v_mov_b32_e32 v152, v120
	v_lshl_add_u64 v[86:87], v[152:153], 2, v[80:81]
	v_add_co_u32_e32 v86, vcc, 0x2ffe000, v86
	s_nop 1
	v_addc_co_u32_e32 v87, vcc, 0, v87, vcc
	global_store_dwordx4 v[86:87], v[76:79], off

.LBB0_866:
	s_or_b64 exec, exec, s[26:27]
	v_or_b32_e32 v66, 64, v122
	v_ashrrev_i32_e32 v67, 31, v66
	v_lshl_add_u64 v[64:65], v[66:67], 2, s[0:1]
	v_mov_b32_e32 v64, v249
	v_fmamk_f32 v64, v64, 0x3a800000, v167
	v_mul_f32_e32 v65, 0x4b800000, v64
	v_cmp_gt_f32_e32 vcc, s42, v64
	s_nop 1
	v_cndmask_b32_e32 v64, v64, v65, vcc
	v_rsq_f32_e32 v68, v64
	v_mov_b64_e32 v[64:65], s[72:73]
	v_mad_i64_i32 v[64:65], s[26:27], v66, s41, v[64:65]
	v_mul_f32_e32 v69, 0x45800000, v68
	v_cndmask_b32_e32 v68, v68, v69, vcc
	v_mul_f32_e32 v71, v60, v68
	v_mul_f32_e32 v70, v61, v68
	v_mul_f32_e32 v69, v62, v68
	v_mul_f32_e32 v62, v63, v68
	s_and_saveexec_b64 s[26:27], s[10:11]
	s_xor_b64 s[26:27], exec, s[26:27]
	s_cbranch_execz .LBB0_870
	v_cmp_gt_u32_e32 vcc, s44, v120
	s_and_saveexec_b64 s[36:37], vcc
	s_cbranch_execz .LBB0_869
	v_mul_f32_e32 v60, 0xbfb8aa3b, v71
	v_mul_f32_e32 v61, 0xbfb8aa3b, v70
	v_mul_f32_e32 v63, 0xbfb8aa3b, v69
	v_mul_f32_e32 v62, 0xbfb8aa3b, v62
	v_exp_f32_e32 v60, v60
	v_exp_f32_e32 v61, v61
	v_exp_f32_e32 v63, v63
	v_exp_f32_e32 v69, v62
	v_add_f32_e32 v60, 1.0, v60
	v_add_f32_e32 v61, 1.0, v61
	v_add_f32_e32 v62, 1.0, v63
	v_add_f32_e32 v63, 1.0, v69
	v_rcp_f32_e32 v60, v60
	v_rcp_f32_e32 v61, v61
	v_rcp_f32_e32 v62, v62
	v_rcp_f32_e32 v63, v63
	v_mov_b32_e32 v152, v120
	v_lshl_add_u64 v[70:71], v[152:153], 2, v[64:65]
	v_add_co_u32_e32 v70, vcc, 0x2ffe000, v70
	s_nop 1
	v_addc_co_u32_e32 v71, vcc, 0, v71, vcc
	global_store_dwordx4 v[70:71], v[60:63], off

.LBB0_890:
	s_or_b64 exec, exec, s[26:27]
	v_or_b32_e32 v50, 0x50, v122
	v_ashrrev_i32_e32 v51, 31, v50
	v_lshl_add_u64 v[48:49], v[50:51], 2, s[0:1]
	v_mov_b32_e32 v48, v250
	v_fmamk_f32 v48, v48, 0x3a800000, v167
	v_mul_f32_e32 v49, 0x4b800000, v48
	v_cmp_gt_f32_e32 vcc, s42, v48
	s_nop 1
	v_cndmask_b32_e32 v48, v48, v49, vcc
	v_rsq_f32_e32 v52, v48
	v_mov_b64_e32 v[48:49], s[72:73]
	v_mad_i64_i32 v[48:49], s[26:27], v50, s41, v[48:49]
	v_mul_f32_e32 v53, 0x45800000, v52
	v_cndmask_b32_e32 v52, v52, v53, vcc
	v_mul_f32_e32 v55, v44, v52
	v_mul_f32_e32 v54, v45, v52
	v_mul_f32_e32 v53, v46, v52
	v_mul_f32_e32 v46, v47, v52
	s_and_saveexec_b64 s[26:27], s[10:11]
	s_xor_b64 s[26:27], exec, s[26:27]
	s_cbranch_execz .LBB0_894
	v_cmp_gt_u32_e32 vcc, s44, v120
	s_and_saveexec_b64 s[36:37], vcc
	s_cbranch_execz .LBB0_893
	v_mul_f32_e32 v44, 0xbfb8aa3b, v55
	v_mul_f32_e32 v45, 0xbfb8aa3b, v54
	v_mul_f32_e32 v47, 0xbfb8aa3b, v53
	v_mul_f32_e32 v46, 0xbfb8aa3b, v46
	v_exp_f32_e32 v44, v44
	v_exp_f32_e32 v45, v45
	v_exp_f32_e32 v47, v47
	v_exp_f32_e32 v53, v46
	v_add_f32_e32 v44, 1.0, v44
	v_add_f32_e32 v45, 1.0, v45
	v_add_f32_e32 v46, 1.0, v47
	v_add_f32_e32 v47, 1.0, v53
	v_rcp_f32_e32 v44, v44
	v_rcp_f32_e32 v45, v45
	v_rcp_f32_e32 v46, v46
	v_rcp_f32_e32 v47, v47
	v_mov_b32_e32 v152, v120
	v_lshl_add_u64 v[54:55], v[152:153], 2, v[48:49]
	v_add_co_u32_e32 v54, vcc, 0x2ffe000, v54
	s_nop 1
	v_addc_co_u32_e32 v55, vcc, 0, v55, vcc
	global_store_dwordx4 v[54:55], v[44:47], off

.LBB0_914:
	s_or_b64 exec, exec, s[26:27]
	v_or_b32_e32 v34, 0x60, v122
	v_ashrrev_i32_e32 v35, 31, v34
	v_lshl_add_u64 v[32:33], v[34:35], 2, s[0:1]
	v_mov_b32_e32 v32, v251
	v_fmamk_f32 v32, v32, 0x3a800000, v167
	v_mul_f32_e32 v33, 0x4b800000, v32
	v_cmp_gt_f32_e32 vcc, s42, v32
	s_nop 1
	v_cndmask_b32_e32 v32, v32, v33, vcc
	v_rsq_f32_e32 v36, v32
	v_mov_b64_e32 v[32:33], s[72:73]
	v_mad_i64_i32 v[32:33], s[26:27], v34, s41, v[32:33]
	v_mul_f32_e32 v37, 0x45800000, v36
	v_cndmask_b32_e32 v36, v36, v37, vcc
	v_mul_f32_e32 v39, v28, v36
	v_mul_f32_e32 v38, v29, v36
	v_mul_f32_e32 v37, v30, v36
	v_mul_f32_e32 v30, v31, v36
	s_and_saveexec_b64 s[26:27], s[10:11]
	s_xor_b64 s[26:27], exec, s[26:27]
	s_cbranch_execz .LBB0_918
	v_cmp_gt_u32_e32 vcc, s44, v120
	s_and_saveexec_b64 s[36:37], vcc
	s_cbranch_execz .LBB0_917
	v_mul_f32_e32 v28, 0xbfb8aa3b, v39
	v_mul_f32_e32 v29, 0xbfb8aa3b, v38
	v_mul_f32_e32 v31, 0xbfb8aa3b, v37
	v_mul_f32_e32 v30, 0xbfb8aa3b, v30
	v_exp_f32_e32 v28, v28
	v_exp_f32_e32 v29, v29
	v_exp_f32_e32 v31, v31
	v_exp_f32_e32 v37, v30
	v_add_f32_e32 v28, 1.0, v28
	v_add_f32_e32 v29, 1.0, v29
	v_add_f32_e32 v30, 1.0, v31
	v_add_f32_e32 v31, 1.0, v37
	v_rcp_f32_e32 v28, v28
	v_rcp_f32_e32 v29, v29
	v_rcp_f32_e32 v30, v30
	v_rcp_f32_e32 v31, v31
	v_mov_b32_e32 v152, v120
	v_lshl_add_u64 v[38:39], v[152:153], 2, v[32:33]
	v_add_co_u32_e32 v38, vcc, 0x2ffe000, v38
	s_nop 1
	v_addc_co_u32_e32 v39, vcc, 0, v39, vcc
	global_store_dwordx4 v[38:39], v[28:31], off

.LBB0_938:
	s_or_b64 exec, exec, s[26:27]
	v_or_b32_e32 v18, 0x70, v122
	v_ashrrev_i32_e32 v19, 31, v18
	v_lshl_add_u64 v[16:17], v[18:19], 2, s[0:1]
	v_mov_b32_e32 v16, v252
	v_fmamk_f32 v16, v16, 0x3a800000, v167
	v_mul_f32_e32 v17, 0x4b800000, v16
	v_cmp_gt_f32_e32 vcc, s42, v16
	s_nop 1
	v_cndmask_b32_e32 v16, v16, v17, vcc
	v_rsq_f32_e32 v20, v16
	v_mov_b64_e32 v[16:17], s[72:73]
	v_mad_i64_i32 v[16:17], s[26:27], v18, s41, v[16:17]
	v_mul_f32_e32 v21, 0x45800000, v20
	v_cndmask_b32_e32 v20, v20, v21, vcc
	v_mul_f32_e32 v23, v12, v20
	v_mul_f32_e32 v22, v13, v20
	v_mul_f32_e32 v21, v14, v20
	v_mul_f32_e32 v14, v15, v20
	s_and_saveexec_b64 s[26:27], s[10:11]
	s_xor_b64 s[10:11], exec, s[26:27]
	s_cbranch_execz .LBB0_942
	v_cmp_gt_u32_e32 vcc, s44, v120
	s_and_saveexec_b64 s[26:27], vcc
	s_cbranch_execz .LBB0_941
	v_mul_f32_e32 v12, 0xbfb8aa3b, v23
	v_mul_f32_e32 v13, 0xbfb8aa3b, v22
	v_mul_f32_e32 v15, 0xbfb8aa3b, v21
	v_mul_f32_e32 v14, 0xbfb8aa3b, v14
	v_exp_f32_e32 v12, v12
	v_exp_f32_e32 v13, v13
	v_exp_f32_e32 v15, v15
	v_exp_f32_e32 v21, v14
	v_add_f32_e32 v12, 1.0, v12
	v_add_f32_e32 v13, 1.0, v13
	v_add_f32_e32 v14, 1.0, v15
	v_add_f32_e32 v15, 1.0, v21
	v_rcp_f32_e32 v12, v12
	v_rcp_f32_e32 v13, v13
	v_rcp_f32_e32 v14, v14
	v_rcp_f32_e32 v15, v15
	v_mov_b32_e32 v152, v120
	v_lshl_add_u64 v[22:23], v[152:153], 2, v[16:17]
	v_add_co_u32_e32 v22, vcc, 0x2ffe000, v22
	s_nop 1
	v_addc_co_u32_e32 v23, vcc, 0, v23, vcc
	global_store_dwordx4 v[22:23], v[12:15], off
